# v047 with the P3 static priority raise at level 3 instead of 2
# speedup vs baseline: 1.0067x; 1.0067x over previous
; __device__ __forceinline__ void xcd_barrier(unsigned* bar, volatile LAS unsigned* st, bool leader, unsigned G) {
;     ...
;     __syncthreads();
; __global__ void __launch_bounds__(512, 2) hybrid_fwd(Params p) {
;     ...
;         if (PH(3)) { PHB
;             if (c < 128) {
;                 const int u = c;
;                     const int qb = 31 - (u >> 2), hd = u & 3, tq0 = 256 * qb + 32 * wave, t_row = tq0 + (lane & 31);
.LBB0_533:
	s_or_b64 exec, exec, s[0:1]
	v_readlane_b32 s0, v255, 0
	s_mov_b32 s70, s23
	s_mov_b32 s2, s0
	v_mov_b32_e32 v144, v234
	s_waitcnt lgkmcnt(0)
	s_barrier
	s_mov_b64 s[8:9], s[50:51]
	v_readfirstlane_b32 s15, v144
	s_ashr_i32 s3, s15, 6
	s_cmp_lt_u32 s3, 4
	s_cbranch_scc0 .Lp3_prio_skip
	s_setprio 3
